# static s_setprio 1 for waves 4-7 during both work-queue phases (attention + chunked scans), reset at phase end
# speedup vs baseline: 1.0132x; 1.0021x over previous
.LBB0_646:
	s_or_b64 exec, exec, s[4:5]
	s_waitcnt lgkmcnt(0)
	s_barrier
	v_readfirstlane_b32 s30, v148
	s_lshr_b32 s30, s30, 6
	s_cmp_ge_u32 s30, 4
	s_cbranch_scc0 .Lprio_q1_skip
	s_setprio 1
.Lprio_q1_skip:
	s_branch .LBB0_649
.LBB0_647:
	s_mov_b64 s[4:5], 0

.LBB0_794:
	s_setprio 0
	s_waitcnt vmcnt(0)
	s_waitcnt lgkmcnt(0)
	s_barrier
	s_mov_b64 s[4:5], exec
	v_readlane_b32 s6, v253, 6
	v_readlane_b32 s7, v253, 7
	s_and_b64 s[6:7], s[4:5], s[6:7]
	s_mov_b64 exec, s[6:7]
	s_cbranch_execz .LBB0_846
	v_readlane_b32 s6, v254, 49
	s_waitcnt vmcnt(0) expcnt(0) lgkmcnt(0)
	s_nop 0
	v_mov_b32_e32 v0, s6
	ds_read_b32 v2, v0
	v_readlane_b32 s6, v254, 50
	s_waitcnt lgkmcnt(0)
	v_cmp_ne_u32_e32 vcc, 0, v2
	v_mov_b32_e32 v0, s6
	ds_read_b32 v0, v0
	s_cbranch_vccnz .LBB0_810
	s_mov_b32 s6, 1
	s_branch .LBB0_798

.Lprio_q0_skip:
	s_branch .LBB0_929
.LBB0_927:
	s_mov_b64 s[4:5], 0
